# GEMM3 tile order: blocks on XCDs 4-7 process their half-height unit first (others last), staggering tile/epilogue boundaries between XCD halves; same work
# speedup vs baseline: 1.0023x; 1.0023x over previous
.LBB0_1116:
	s_add_u32 s10, s28, 0x3b00000
	s_addc_u32 s11, s29, 0
	s_abs_i32 s33, s84
	s_waitcnt vmcnt(0)
	v_cvt_f32_u32_e32 v0, s33
	s_sub_i32 s0, 0, s33
	s_ashr_i32 s42, s84, 31
	v_rcp_iflag_f32_e32 v1, v0
	v_mov_b32_e32 v0, v224
	v_mul_f32_e32 v1, 0x4f7ffffe, v1
	v_cvt_u32_f32_e32 v1, v1
	s_nop 0
	v_readfirstlane_b32 s43, v1
	s_mul_i32 s0, s0, s43
	s_mul_hi_u32 s0, s43, s0
	s_add_i32 s43, s43, s0
	s_mul_hi_u32 s0, s43, 0x580
	s_mul_i32 s0, s0, s33
	s_sub_i32 s0, 0x580, s0
	s_sub_i32 s1, s0, s33
	s_cmp_ge_u32 s0, s33
	s_cselect_b32 s0, s1, s0
	s_sub_i32 s1, s0, s33
	s_cmp_ge_u32 s0, s33
	s_cselect_b32 s4, s1, s0
	s_cmp_lg_u32 s4, 0
	s_cselect_b64 s[0:1], -1, 0
	s_lshl_b32 s5, s4, 1
	s_cmp_le_i32 s5, s84
	s_cselect_b64 s[2:3], -1, 0
	s_sub_i32 s4, 0x580, s4
	s_and_b64 s[0:1], s[0:1], s[2:3]
	s_and_b64 s[0:1], s[0:1], exec
	s_cselect_b32 s54, s4, 0x580
	s_cselect_b32 s0, s5, 0
	s_add_i32 s55, s54, s0
	s_cmp_ge_i32 s66, s55
	v_readfirstlane_b32 s2, v0
	s_cbranch_scc1 .LBB0_1183
	v_lshlrev_b32_e32 v2, 4, v0
	v_add_u32_e32 v3, 0x2000, v2
	v_ashrrev_i32_e32 v4, 31, v3
	v_lshrrev_b32_e32 v4, 22, v4
	v_add_u32_e32 v4, v3, v4
	v_ashrrev_i32_e32 v4, 10, v4
	v_mul_i32_i24_e32 v6, 0x400, v4
	v_sub_u32_e32 v3, v3, v6
	v_lshrrev_b32_e32 v6, 4, v3
	v_bitop3_b32 v3, v6, v3, 32 bitop3:0x6c
	v_ashrrev_i32_e32 v6, 31, v3
	v_lshrrev_b32_e32 v6, 26, v6
	v_add_u32_e32 v6, v3, v6
	v_lshrrev_b32_e32 v7, 6, v6
	v_and_b32_e32 v6, 0xc0, v6
	v_lshlrev_b32_e32 v5, 5, v4
	v_sub_u32_e32 v3, v3, v6
	v_mov_b32_e32 v6, 1
	v_and_b32_e32 v5, 32, v5
	v_ashrrev_i16_sdwa v3, v6, sext(v3) dst_sel:DWORD dst_unused:UNUSED_PAD src0_sel:DWORD src1_sel:BYTE_0
	v_add_u32_sdwa v3, v5, sext(v3) dst_sel:DWORD dst_unused:UNUSED_PAD src0_sel:DWORD src1_sel:WORD_0
	v_bfe_i32 v5, v0, 27, 1
	v_lshrrev_b32_e32 v5, 22, v5
	v_add_u32_e32 v5, v2, v5
	v_lshlrev_b32_e32 v4, 3, v4
	v_and_b32_e32 v5, 0xfffffc00, v5
	v_and_b32_e32 v4, 0xffff0, v4
	v_sub_u32_e32 v5, v2, v5
	v_add_lshl_u32 v4, v7, v4, 12
	v_lshrrev_b32_e32 v7, 4, v5
	v_bitop3_b32 v5, v7, v5, 32 bitop3:0x6c
	v_lshl_add_u32 v226, v3, 1, v4
	v_ashrrev_i32_e32 v3, 31, v0
	v_ashrrev_i32_e32 v7, 31, v5
	v_lshrrev_b32_e32 v3, 26, v3
	v_lshrrev_b32_e32 v7, 26, v7
	s_add_u32 s56, s28, 0x6700000
	v_add_u32_e32 v3, v0, v3
	v_add_u32_e32 v7, v5, v7
	s_addc_u32 s57, s29, 0
	v_ashrrev_i32_e32 v3, 6, v3
	v_lshrrev_b32_e32 v8, 6, v7
	v_and_b32_e32 v7, 0xc0, v7
	s_bfe_u32 s3, s2, 0x20006
	s_ashr_i32 s4, s2, 8
	v_lshlrev_b32_e32 v4, 5, v3
	v_sub_u32_e32 v5, v5, v7
	v_lshlrev_b32_e32 v3, 3, v3
	s_cmp_eq_u32 s4, 1
	v_and_b32_e32 v4, 32, v4
	v_ashrrev_i16_sdwa v5, v6, sext(v5) dst_sel:DWORD dst_unused:UNUSED_PAD src0_sel:DWORD src1_sel:BYTE_0
	v_and_b32_e32 v3, 0xffff0, v3
	s_cselect_b64 s[0:1], -1, 0
	s_lshl_b32 s5, s3, 12
	s_add_i32 s6, 16, 0x10000
	s_add_i32 s7, 16, 0x14000
	s_add_i32 s18, 16, 0x18000
	s_add_i32 s19, 16, 0x1c000
	v_add_u32_sdwa v4, v4, sext(v5) dst_sel:DWORD dst_unused:UNUSED_PAD src0_sel:DWORD src1_sel:WORD_0
	v_add_lshl_u32 v3, v8, v3, 12
	s_cmpk_lt_u32 s2, 0x100
	v_and_b32_e32 v1, 15, v0
	v_lshl_add_u32 v228, v4, 1, v3
	v_bfe_u32 v3, v0, 4, 2
	s_cselect_b64 s[12:13], -1, 0
	s_lshl_b32 s2, s3, 7
	v_lshlrev_b32_e32 v4, 4, v3
	v_lshlrev_b32_e32 v5, 6, v1
	v_lshlrev_b32_e32 v1, 2, v1
	v_mul_u32_u24_e32 v3, 0x1040, v3
	s_add_i32 s2, s2, 16
	v_add3_u32 v225, s2, v3, v1
	s_lshl_b32 s2, s4, 13
	s_or_b32 s58, s2, 0x800
	s_or_b32 s59, s2, 0x1000
	s_or_b32 s60, s2, 0x1800
	v_and_b32_e32 v6, 32, v1
	s_add_u32 s14, s28, 0x8700000
	v_bitop3_b32 v5, v4, v6, v5 bitop3:0x36
	v_lshlrev_b32_e32 v0, 6, v0
	s_movk_i32 s3, 0x3c0
	s_addc_u32 s15, s29, 0
	v_add_u32_e32 v7, s6, v5
	v_add_u32_e32 v8, s7, v5
	v_add_u32_e32 v9, s18, v5
	v_add_u32_e32 v10, s19, v5
	v_add_u32_e32 v1, 16, v5
	v_and_or_b32 v0, v0, s3, v4
	s_add_u32 s61, s28, 0xdf00000
	v_add_u32_e32 v231, 16, v2
	v_add_u32_e32 v236, s6, v2
	v_add_u32_e32 v238, s7, v2
	v_add_u32_e32 v240, s18, v2
	v_add_u32_e32 v244, s19, v2
	v_xad_u32 v230, v0, v6, 16
	s_addc_u32 s62, s29, 0
	v_mov_b32_e32 v229, 0
	v_add_u32_e32 v232, 0x2000, v231
	v_add_u32_e32 v233, 0x4000, v231
	v_add_u32_e32 v234, 0x6000, v231
	v_cndmask_b32_e64 v235, 0, 1, s[0:1]
	s_mov_b64 s[16:17], 0x80
	s_mov_b64 s[34:35], 0x6700080
	s_mov_b64 s[36:37], 0x3b00100
	s_mov_b64 s[38:39], 0x6700100
	s_mov_b64 s[40:41], 0x3b80100
	s_mov_b64 s[44:45], 0x3b00180
	s_mov_b64 s[46:47], 0x6700180
	s_mov_b64 s[48:49], 0x3b80180
	s_mov_b64 s[50:51], 0xf80
	s_movk_i32 s63, 0xbf
	s_movk_i32 s64, 0x2c00
	s_add_i32 s65, 16, 0x10400
	s_add_i32 s66, 16, 0x10800
	s_add_i32 s67, 16, 0x10c00
	s_add_i32 s68, 16, 0x10600
	s_add_i32 s69, 16, 0x10a00
	s_add_i32 s70, 16, 0x10e00
	s_movk_i32 s71, 0x410
	s_add_i32 s72, 16, 0xfffffbf0
	s_movk_i32 s73, 0xffc4
	s_movk_i32 s74, 0x5800
	v_add_u32_e32 v237, 0x2000, v236
	v_add_u32_e32 v239, 0x2000, v238
	v_add_u32_e32 v241, 0x2000, v240
	v_add_u32_e32 v242, 0x8000, v231
	v_add_u32_e32 v243, 0xa000, v231
	v_add_u32_e32 v245, 0x2000, v244
	v_add_u32_e32 v246, s5, v7
	v_add_u32_e32 v247, s2, v1
	v_add_u32_e32 v248, s5, v8
	v_add_u32_e32 v249, s5, v9
	v_add_u32_e32 v250, s5, v10
	v_readlane_b32 s75, v255, 46
	s_nop 3
	s_mov_b32 s100, 0
	s_mov_b32 s99, s75
.Lmy_g3_cnt:
	s_add_i32 s100, s100, 1
	s_add_i32 s99, s99, s84
	s_cmp_lt_i32 s99, s55
	s_cbranch_scc1 .Lmy_g3_cnt
	s_mov_b32 s98, s100
	s_mul_i32 s101, s100, s84
	s_sub_i32 s99, s99, s84
	s_bitcmp1_b32 s75, 2
	s_cbranch_scc0 .Lmy_g3_go
	s_cmp_lt_i32 s99, s54
	s_cbranch_scc1 .Lmy_g3_go
	s_mov_b32 s75, s99
.Lmy_g3_go:
	s_branch .LBB0_1120

.LBB0_1119:
	s_sub_i32 s98, s98, 1
	s_cmp_eq_u32 s98, 0
	s_cbranch_scc1 .LBB0_1183
	s_add_i32 s75, s75, s84
	s_cmp_lt_i32 s75, s55
	s_cbranch_scc1 .LBB0_1120
	s_sub_i32 s75, s75, s101
